# hand-written phase_final: 8 rows per wave, all row loads issued up front, DPP+readlane reduction
# baseline (speedup 1.0000x reference)
; __device__ __forceinline__ void phase_final(KP kp_){ asm volatile("" : "+s"(kp_)); const Params p=load_params(kp_);
;     ...
;   for (int r=blockIdx.x*8+wid; r<16384; r+=gridDim.x*8){
;     float4 xv[4]; float ss=0.f;
;     for(int i=0;i<4;++i){ xv[i]=*(const float4*)(p.out+(size_t)r*1024+lane*4+256*i); ss+=xv[i].x*xv[i].x+xv[i].y*xv[i].y+xv[i].z*xv[i].z+xv[i].w*xv[i].w; }
;     ss=wave_sum(ss); float rstd=rsqrtf(ss*(1.f/1024.f)+EPSV);
;     for(int i=0;i<4;++i){ int col=lane*4+256*i; float4 v=xv[i]; float4 g=*(const float4*)(p.final_g+col);
;       v.x*=rstd*g.x; v.y*=rstd*g.y; v.z*=rstd*g.z; v.w*=rstd*g.w; *(float4*)(p.out+(size_t)r*1024+col)=v; }
.LBB0_1553:
	s_or_b64 exec, exec, s[0:1]
	s_waitcnt lgkmcnt(0)
	s_barrier
	s_load_dwordx4 s[0:3], s[78:79], 0xd0
	v_readlane_b32 s4, v253, 37
	v_and_b32_e32 v1, 63, v154
	v_lshrrev_b32_e32 v2, 6, v154
	v_lshlrev_b32_e32 v3, 4, v1
	v_readfirstlane_b32 s5, v2
	v_mov_b32_e32 v6, 0x358637bd
	s_add_u32 s4, s4, s5
	s_lshl_b32 s5, s4, 12
	v_add_u32_e32 v4, s5, v3
	s_waitcnt lgkmcnt(0)
	global_load_dwordx4 v[8:11], v3, s[0:1] offset:0
	global_load_dwordx4 v[12:15], v3, s[0:1] offset:1024
	global_load_dwordx4 v[16:19], v3, s[0:1] offset:2048
	global_load_dwordx4 v[20:23], v3, s[0:1] offset:3072
	global_load_dwordx4 v[24:27], v4, s[2:3] offset:0
	global_load_dwordx4 v[28:31], v4, s[2:3] offset:1024
	global_load_dwordx4 v[32:35], v4, s[2:3] offset:2048
	global_load_dwordx4 v[36:39], v4, s[2:3] offset:3072
	s_add_u32 s6, s2, 0x800000
	s_addc_u32 s7, s3, 0
	global_load_dwordx4 v[40:43], v4, s[6:7] offset:0
	global_load_dwordx4 v[44:47], v4, s[6:7] offset:1024
	global_load_dwordx4 v[48:51], v4, s[6:7] offset:2048
	global_load_dwordx4 v[52:55], v4, s[6:7] offset:3072
	s_add_u32 s6, s2, 0x1000000
	s_addc_u32 s7, s3, 0
	global_load_dwordx4 v[56:59], v4, s[6:7] offset:0
	global_load_dwordx4 v[60:63], v4, s[6:7] offset:1024
	global_load_dwordx4 v[64:67], v4, s[6:7] offset:2048
	global_load_dwordx4 v[68:71], v4, s[6:7] offset:3072
	s_add_u32 s6, s2, 0x1800000
	s_addc_u32 s7, s3, 0
	global_load_dwordx4 v[72:75], v4, s[6:7] offset:0
	global_load_dwordx4 v[76:79], v4, s[6:7] offset:1024
	global_load_dwordx4 v[80:83], v4, s[6:7] offset:2048
	global_load_dwordx4 v[84:87], v4, s[6:7] offset:3072
	s_add_u32 s6, s2, 0x2000000
	s_addc_u32 s7, s3, 0
	global_load_dwordx4 v[88:91], v4, s[6:7] offset:0
	global_load_dwordx4 v[92:95], v4, s[6:7] offset:1024
	global_load_dwordx4 v[96:99], v4, s[6:7] offset:2048
	global_load_dwordx4 v[100:103], v4, s[6:7] offset:3072
	s_add_u32 s6, s2, 0x2800000
	s_addc_u32 s7, s3, 0
	global_load_dwordx4 v[104:107], v4, s[6:7] offset:0
	global_load_dwordx4 v[108:111], v4, s[6:7] offset:1024
	global_load_dwordx4 v[112:115], v4, s[6:7] offset:2048
	global_load_dwordx4 v[116:119], v4, s[6:7] offset:3072
	s_add_u32 s6, s2, 0x3000000
	s_addc_u32 s7, s3, 0
	global_load_dwordx4 v[120:123], v4, s[6:7] offset:0
	global_load_dwordx4 v[124:127], v4, s[6:7] offset:1024
	global_load_dwordx4 v[128:131], v4, s[6:7] offset:2048
	global_load_dwordx4 v[132:135], v4, s[6:7] offset:3072
	s_add_u32 s6, s2, 0x3800000
	s_addc_u32 s7, s3, 0
	global_load_dwordx4 v[136:139], v4, s[6:7] offset:0
	global_load_dwordx4 v[140:143], v4, s[6:7] offset:1024
	global_load_dwordx4 v[144:147], v4, s[6:7] offset:2048
	global_load_dwordx4 v[148:151], v4, s[6:7] offset:3072
	s_waitcnt vmcnt(28)
	v_mul_f32_e32 v5, v24, v24
	v_fmac_f32_e32 v5, v25, v25
	v_fmac_f32_e32 v5, v26, v26
	v_fmac_f32_e32 v5, v27, v27
	v_fmac_f32_e32 v5, v28, v28
	v_fmac_f32_e32 v5, v29, v29
	v_fmac_f32_e32 v5, v30, v30
	v_fmac_f32_e32 v5, v31, v31
	v_fmac_f32_e32 v5, v32, v32
	v_fmac_f32_e32 v5, v33, v33
	v_fmac_f32_e32 v5, v34, v34
	v_fmac_f32_e32 v5, v35, v35
	v_fmac_f32_e32 v5, v36, v36
	v_fmac_f32_e32 v5, v37, v37
	v_fmac_f32_e32 v5, v38, v38
	v_fmac_f32_e32 v5, v39, v39
	s_nop 1
	v_add_f32_dpp v5, v5, v5 row_ror:8 row_mask:0xf bank_mask:0xf
	s_nop 1
	v_add_f32_dpp v5, v5, v5 row_ror:4 row_mask:0xf bank_mask:0xf
	s_nop 1
	v_add_f32_dpp v5, v5, v5 row_ror:2 row_mask:0xf bank_mask:0xf
	s_nop 1
	v_add_f32_dpp v5, v5, v5 row_ror:1 row_mask:0xf bank_mask:0xf
	s_nop 1
	v_readlane_b32 s8, v5, 0
	v_readlane_b32 s9, v5, 16
	v_readlane_b32 s10, v5, 32
	v_readlane_b32 s11, v5, 48
	s_nop 1
	v_mov_b32_e32 v7, s8
	v_add_f32_e32 v7, s9, v7
	v_add_f32_e32 v7, s10, v7
	v_add_f32_e32 v7, s11, v7
	v_fmamk_f32 v7, v7, 0x3a800000, v6
	v_rsq_f32_e32 v152, v7
	s_nop 0
	v_mul_f32_e32 v153, v152, v8
	v_mul_f32_e32 v24, v24, v153
	v_mul_f32_e32 v153, v152, v9
	v_mul_f32_e32 v25, v25, v153
	v_mul_f32_e32 v153, v152, v10
	v_mul_f32_e32 v26, v26, v153
	v_mul_f32_e32 v153, v152, v11
	v_mul_f32_e32 v27, v27, v153
	global_store_dwordx4 v4, v[24:27], s[2:3] offset:0
	v_mul_f32_e32 v153, v152, v12
	v_mul_f32_e32 v28, v28, v153
	v_mul_f32_e32 v153, v152, v13
	v_mul_f32_e32 v29, v29, v153
	v_mul_f32_e32 v153, v152, v14
	v_mul_f32_e32 v30, v30, v153
	v_mul_f32_e32 v153, v152, v15
	v_mul_f32_e32 v31, v31, v153
	global_store_dwordx4 v4, v[28:31], s[2:3] offset:1024
	v_mul_f32_e32 v153, v152, v16
	v_mul_f32_e32 v32, v32, v153
	v_mul_f32_e32 v153, v152, v17
	v_mul_f32_e32 v33, v33, v153
	v_mul_f32_e32 v153, v152, v18
	v_mul_f32_e32 v34, v34, v153
	v_mul_f32_e32 v153, v152, v19
	v_mul_f32_e32 v35, v35, v153
	global_store_dwordx4 v4, v[32:35], s[2:3] offset:2048
	v_mul_f32_e32 v153, v152, v20
	v_mul_f32_e32 v36, v36, v153
	v_mul_f32_e32 v153, v152, v21
	v_mul_f32_e32 v37, v37, v153
	v_mul_f32_e32 v153, v152, v22
	v_mul_f32_e32 v38, v38, v153
	v_mul_f32_e32 v153, v152, v23
	v_mul_f32_e32 v39, v39, v153
	global_store_dwordx4 v4, v[36:39], s[2:3] offset:3072
	s_waitcnt vmcnt(28)
; __device__ __forceinline__ void phase_final(KP kp_){ asm volatile("" : "+s"(kp_)); const Params p=load_params(kp_);
;     ...
;   for (int r=blockIdx.x*8+wid; r<16384; r+=gridDim.x*8){
;     float4 xv[4]; float ss=0.f;
;     for(int i=0;i<4;++i){ xv[i]=*(const float4*)(p.out+(size_t)r*1024+lane*4+256*i); ss+=xv[i].x*xv[i].x+xv[i].y*xv[i].y+xv[i].z*xv[i].z+xv[i].w*xv[i].w; }
;     ss=wave_sum(ss); float rstd=rsqrtf(ss*(1.f/1024.f)+EPSV);
;     for(int i=0;i<4;++i){ int col=lane*4+256*i; float4 v=xv[i]; float4 g=*(const float4*)(p.final_g+col);
;       v.x*=rstd*g.x; v.y*=rstd*g.y; v.z*=rstd*g.z; v.w*=rstd*g.w; *(float4*)(p.out+(size_t)r*1024+col)=v; }
	v_mul_f32_e32 v5, v40, v40
	v_fmac_f32_e32 v5, v41, v41
	v_fmac_f32_e32 v5, v42, v42
	v_fmac_f32_e32 v5, v43, v43
	v_fmac_f32_e32 v5, v44, v44
	v_fmac_f32_e32 v5, v45, v45
	v_fmac_f32_e32 v5, v46, v46
	v_fmac_f32_e32 v5, v47, v47
	v_fmac_f32_e32 v5, v48, v48
	v_fmac_f32_e32 v5, v49, v49
	v_fmac_f32_e32 v5, v50, v50
	v_fmac_f32_e32 v5, v51, v51
	v_fmac_f32_e32 v5, v52, v52
	v_fmac_f32_e32 v5, v53, v53
	v_fmac_f32_e32 v5, v54, v54
	v_fmac_f32_e32 v5, v55, v55
	s_nop 1
	v_add_f32_dpp v5, v5, v5 row_ror:8 row_mask:0xf bank_mask:0xf
	s_nop 1
	v_add_f32_dpp v5, v5, v5 row_ror:4 row_mask:0xf bank_mask:0xf
	s_nop 1
	v_add_f32_dpp v5, v5, v5 row_ror:2 row_mask:0xf bank_mask:0xf
	s_nop 1
	v_add_f32_dpp v5, v5, v5 row_ror:1 row_mask:0xf bank_mask:0xf
	s_nop 1
	v_readlane_b32 s8, v5, 0
	v_readlane_b32 s9, v5, 16
	v_readlane_b32 s10, v5, 32
	v_readlane_b32 s11, v5, 48
	s_nop 1
	v_mov_b32_e32 v7, s8
	v_add_f32_e32 v7, s9, v7
	v_add_f32_e32 v7, s10, v7
	v_add_f32_e32 v7, s11, v7
	v_fmamk_f32 v7, v7, 0x3a800000, v6
	v_rsq_f32_e32 v152, v7
	s_nop 0
	s_add_u32 s6, s2, 0x800000
	s_addc_u32 s7, s3, 0
	v_mul_f32_e32 v153, v152, v8
	v_mul_f32_e32 v40, v40, v153
	v_mul_f32_e32 v153, v152, v9
	v_mul_f32_e32 v41, v41, v153
	v_mul_f32_e32 v153, v152, v10
	v_mul_f32_e32 v42, v42, v153
	v_mul_f32_e32 v153, v152, v11
	v_mul_f32_e32 v43, v43, v153
	global_store_dwordx4 v4, v[40:43], s[6:7] offset:0
	v_mul_f32_e32 v153, v152, v12
	v_mul_f32_e32 v44, v44, v153
	v_mul_f32_e32 v153, v152, v13
	v_mul_f32_e32 v45, v45, v153
	v_mul_f32_e32 v153, v152, v14
	v_mul_f32_e32 v46, v46, v153
	v_mul_f32_e32 v153, v152, v15
	v_mul_f32_e32 v47, v47, v153
	global_store_dwordx4 v4, v[44:47], s[6:7] offset:1024
	v_mul_f32_e32 v153, v152, v16
	v_mul_f32_e32 v48, v48, v153
	v_mul_f32_e32 v153, v152, v17
	v_mul_f32_e32 v49, v49, v153
	v_mul_f32_e32 v153, v152, v18
	v_mul_f32_e32 v50, v50, v153
	v_mul_f32_e32 v153, v152, v19
	v_mul_f32_e32 v51, v51, v153
	global_store_dwordx4 v4, v[48:51], s[6:7] offset:2048
	v_mul_f32_e32 v153, v152, v20
	v_mul_f32_e32 v52, v52, v153
	v_mul_f32_e32 v153, v152, v21
	v_mul_f32_e32 v53, v53, v153
	v_mul_f32_e32 v153, v152, v22
	v_mul_f32_e32 v54, v54, v153
	v_mul_f32_e32 v153, v152, v23
	v_mul_f32_e32 v55, v55, v153
	global_store_dwordx4 v4, v[52:55], s[6:7] offset:3072
	s_waitcnt vmcnt(28)
	v_mul_f32_e32 v5, v56, v56
	v_fmac_f32_e32 v5, v57, v57
	v_fmac_f32_e32 v5, v58, v58
	v_fmac_f32_e32 v5, v59, v59
	v_fmac_f32_e32 v5, v60, v60
	v_fmac_f32_e32 v5, v61, v61
	v_fmac_f32_e32 v5, v62, v62
	v_fmac_f32_e32 v5, v63, v63
	v_fmac_f32_e32 v5, v64, v64
	v_fmac_f32_e32 v5, v65, v65
	v_fmac_f32_e32 v5, v66, v66
	v_fmac_f32_e32 v5, v67, v67
	v_fmac_f32_e32 v5, v68, v68
	v_fmac_f32_e32 v5, v69, v69
	v_fmac_f32_e32 v5, v70, v70
	v_fmac_f32_e32 v5, v71, v71
	s_nop 1
	v_add_f32_dpp v5, v5, v5 row_ror:8 row_mask:0xf bank_mask:0xf
	s_nop 1
	v_add_f32_dpp v5, v5, v5 row_ror:4 row_mask:0xf bank_mask:0xf
	s_nop 1
	v_add_f32_dpp v5, v5, v5 row_ror:2 row_mask:0xf bank_mask:0xf
	s_nop 1
	v_add_f32_dpp v5, v5, v5 row_ror:1 row_mask:0xf bank_mask:0xf
	s_nop 1
	v_readlane_b32 s8, v5, 0
	v_readlane_b32 s9, v5, 16
	v_readlane_b32 s10, v5, 32
	v_readlane_b32 s11, v5, 48
	s_nop 1
	v_mov_b32_e32 v7, s8
	v_add_f32_e32 v7, s9, v7
	v_add_f32_e32 v7, s10, v7
	v_add_f32_e32 v7, s11, v7
	v_fmamk_f32 v7, v7, 0x3a800000, v6
	v_rsq_f32_e32 v152, v7
	s_nop 0
	s_add_u32 s6, s2, 0x1000000
	s_addc_u32 s7, s3, 0
	v_mul_f32_e32 v153, v152, v8
	v_mul_f32_e32 v56, v56, v153
	v_mul_f32_e32 v153, v152, v9
	v_mul_f32_e32 v57, v57, v153
	v_mul_f32_e32 v153, v152, v10
	v_mul_f32_e32 v58, v58, v153
	v_mul_f32_e32 v153, v152, v11
	v_mul_f32_e32 v59, v59, v153
	global_store_dwordx4 v4, v[56:59], s[6:7] offset:0
	v_mul_f32_e32 v153, v152, v12
	v_mul_f32_e32 v60, v60, v153
	v_mul_f32_e32 v153, v152, v13
	v_mul_f32_e32 v61, v61, v153
	v_mul_f32_e32 v153, v152, v14
	v_mul_f32_e32 v62, v62, v153
	v_mul_f32_e32 v153, v152, v15
	v_mul_f32_e32 v63, v63, v153
	global_store_dwordx4 v4, v[60:63], s[6:7] offset:1024
	v_mul_f32_e32 v153, v152, v16
	v_mul_f32_e32 v64, v64, v153
	v_mul_f32_e32 v153, v152, v17
	v_mul_f32_e32 v65, v65, v153
	v_mul_f32_e32 v153, v152, v18
	v_mul_f32_e32 v66, v66, v153
	v_mul_f32_e32 v153, v152, v19
	v_mul_f32_e32 v67, v67, v153
	global_store_dwordx4 v4, v[64:67], s[6:7] offset:2048
	v_mul_f32_e32 v153, v152, v20
	v_mul_f32_e32 v68, v68, v153
	v_mul_f32_e32 v153, v152, v21
	v_mul_f32_e32 v69, v69, v153
	v_mul_f32_e32 v153, v152, v22
	v_mul_f32_e32 v70, v70, v153
	v_mul_f32_e32 v153, v152, v23
	v_mul_f32_e32 v71, v71, v153
	global_store_dwordx4 v4, v[68:71], s[6:7] offset:3072
	s_waitcnt vmcnt(28)
; __device__ __forceinline__ void phase_final(KP kp_){ asm volatile("" : "+s"(kp_)); const Params p=load_params(kp_);
;     ...
;   for (int r=blockIdx.x*8+wid; r<16384; r+=gridDim.x*8){
;     float4 xv[4]; float ss=0.f;
;     for(int i=0;i<4;++i){ xv[i]=*(const float4*)(p.out+(size_t)r*1024+lane*4+256*i); ss+=xv[i].x*xv[i].x+xv[i].y*xv[i].y+xv[i].z*xv[i].z+xv[i].w*xv[i].w; }
;     ss=wave_sum(ss); float rstd=rsqrtf(ss*(1.f/1024.f)+EPSV);
;     for(int i=0;i<4;++i){ int col=lane*4+256*i; float4 v=xv[i]; float4 g=*(const float4*)(p.final_g+col);
;       v.x*=rstd*g.x; v.y*=rstd*g.y; v.z*=rstd*g.z; v.w*=rstd*g.w; *(float4*)(p.out+(size_t)r*1024+col)=v; }
	v_mul_f32_e32 v5, v72, v72
	v_fmac_f32_e32 v5, v73, v73
	v_fmac_f32_e32 v5, v74, v74
	v_fmac_f32_e32 v5, v75, v75
	v_fmac_f32_e32 v5, v76, v76
	v_fmac_f32_e32 v5, v77, v77
	v_fmac_f32_e32 v5, v78, v78
	v_fmac_f32_e32 v5, v79, v79
	v_fmac_f32_e32 v5, v80, v80
	v_fmac_f32_e32 v5, v81, v81
	v_fmac_f32_e32 v5, v82, v82
	v_fmac_f32_e32 v5, v83, v83
	v_fmac_f32_e32 v5, v84, v84
	v_fmac_f32_e32 v5, v85, v85
	v_fmac_f32_e32 v5, v86, v86
	v_fmac_f32_e32 v5, v87, v87
	s_nop 1
	v_add_f32_dpp v5, v5, v5 row_ror:8 row_mask:0xf bank_mask:0xf
	s_nop 1
	v_add_f32_dpp v5, v5, v5 row_ror:4 row_mask:0xf bank_mask:0xf
	s_nop 1
	v_add_f32_dpp v5, v5, v5 row_ror:2 row_mask:0xf bank_mask:0xf
	s_nop 1
	v_add_f32_dpp v5, v5, v5 row_ror:1 row_mask:0xf bank_mask:0xf
	s_nop 1
	v_readlane_b32 s8, v5, 0
	v_readlane_b32 s9, v5, 16
	v_readlane_b32 s10, v5, 32
	v_readlane_b32 s11, v5, 48
	s_nop 1
	v_mov_b32_e32 v7, s8
	v_add_f32_e32 v7, s9, v7
	v_add_f32_e32 v7, s10, v7
	v_add_f32_e32 v7, s11, v7
	v_fmamk_f32 v7, v7, 0x3a800000, v6
	v_rsq_f32_e32 v152, v7
	s_nop 0
	s_add_u32 s6, s2, 0x1800000
	s_addc_u32 s7, s3, 0
	v_mul_f32_e32 v153, v152, v8
	v_mul_f32_e32 v72, v72, v153
	v_mul_f32_e32 v153, v152, v9
	v_mul_f32_e32 v73, v73, v153
	v_mul_f32_e32 v153, v152, v10
	v_mul_f32_e32 v74, v74, v153
	v_mul_f32_e32 v153, v152, v11
	v_mul_f32_e32 v75, v75, v153
	global_store_dwordx4 v4, v[72:75], s[6:7] offset:0
	v_mul_f32_e32 v153, v152, v12
	v_mul_f32_e32 v76, v76, v153
	v_mul_f32_e32 v153, v152, v13
	v_mul_f32_e32 v77, v77, v153
	v_mul_f32_e32 v153, v152, v14
	v_mul_f32_e32 v78, v78, v153
	v_mul_f32_e32 v153, v152, v15
	v_mul_f32_e32 v79, v79, v153
	global_store_dwordx4 v4, v[76:79], s[6:7] offset:1024
	v_mul_f32_e32 v153, v152, v16
	v_mul_f32_e32 v80, v80, v153
	v_mul_f32_e32 v153, v152, v17
	v_mul_f32_e32 v81, v81, v153
	v_mul_f32_e32 v153, v152, v18
	v_mul_f32_e32 v82, v82, v153
	v_mul_f32_e32 v153, v152, v19
	v_mul_f32_e32 v83, v83, v153
	global_store_dwordx4 v4, v[80:83], s[6:7] offset:2048
	v_mul_f32_e32 v153, v152, v20
	v_mul_f32_e32 v84, v84, v153
	v_mul_f32_e32 v153, v152, v21
	v_mul_f32_e32 v85, v85, v153
	v_mul_f32_e32 v153, v152, v22
	v_mul_f32_e32 v86, v86, v153
	v_mul_f32_e32 v153, v152, v23
	v_mul_f32_e32 v87, v87, v153
	global_store_dwordx4 v4, v[84:87], s[6:7] offset:3072
	s_waitcnt vmcnt(28)
	v_mul_f32_e32 v5, v88, v88
	v_fmac_f32_e32 v5, v89, v89
	v_fmac_f32_e32 v5, v90, v90
	v_fmac_f32_e32 v5, v91, v91
	v_fmac_f32_e32 v5, v92, v92
	v_fmac_f32_e32 v5, v93, v93
	v_fmac_f32_e32 v5, v94, v94
	v_fmac_f32_e32 v5, v95, v95
	v_fmac_f32_e32 v5, v96, v96
	v_fmac_f32_e32 v5, v97, v97
	v_fmac_f32_e32 v5, v98, v98
	v_fmac_f32_e32 v5, v99, v99
	v_fmac_f32_e32 v5, v100, v100
	v_fmac_f32_e32 v5, v101, v101
	v_fmac_f32_e32 v5, v102, v102
	v_fmac_f32_e32 v5, v103, v103
	s_nop 1
	v_add_f32_dpp v5, v5, v5 row_ror:8 row_mask:0xf bank_mask:0xf
	s_nop 1
	v_add_f32_dpp v5, v5, v5 row_ror:4 row_mask:0xf bank_mask:0xf
	s_nop 1
	v_add_f32_dpp v5, v5, v5 row_ror:2 row_mask:0xf bank_mask:0xf
	s_nop 1
	v_add_f32_dpp v5, v5, v5 row_ror:1 row_mask:0xf bank_mask:0xf
	s_nop 1
	v_readlane_b32 s8, v5, 0
	v_readlane_b32 s9, v5, 16
	v_readlane_b32 s10, v5, 32
	v_readlane_b32 s11, v5, 48
	s_nop 1
	v_mov_b32_e32 v7, s8
	v_add_f32_e32 v7, s9, v7
	v_add_f32_e32 v7, s10, v7
	v_add_f32_e32 v7, s11, v7
	v_fmamk_f32 v7, v7, 0x3a800000, v6
	v_rsq_f32_e32 v152, v7
	s_nop 0
	s_add_u32 s6, s2, 0x2000000
	s_addc_u32 s7, s3, 0
	v_mul_f32_e32 v153, v152, v8
	v_mul_f32_e32 v88, v88, v153
	v_mul_f32_e32 v153, v152, v9
	v_mul_f32_e32 v89, v89, v153
	v_mul_f32_e32 v153, v152, v10
	v_mul_f32_e32 v90, v90, v153
	v_mul_f32_e32 v153, v152, v11
	v_mul_f32_e32 v91, v91, v153
	global_store_dwordx4 v4, v[88:91], s[6:7] offset:0
	v_mul_f32_e32 v153, v152, v12
	v_mul_f32_e32 v92, v92, v153
	v_mul_f32_e32 v153, v152, v13
	v_mul_f32_e32 v93, v93, v153
	v_mul_f32_e32 v153, v152, v14
	v_mul_f32_e32 v94, v94, v153
	v_mul_f32_e32 v153, v152, v15
	v_mul_f32_e32 v95, v95, v153
	global_store_dwordx4 v4, v[92:95], s[6:7] offset:1024
	v_mul_f32_e32 v153, v152, v16
	v_mul_f32_e32 v96, v96, v153
	v_mul_f32_e32 v153, v152, v17
	v_mul_f32_e32 v97, v97, v153
	v_mul_f32_e32 v153, v152, v18
	v_mul_f32_e32 v98, v98, v153
	v_mul_f32_e32 v153, v152, v19
	v_mul_f32_e32 v99, v99, v153
	global_store_dwordx4 v4, v[96:99], s[6:7] offset:2048
	v_mul_f32_e32 v153, v152, v20
	v_mul_f32_e32 v100, v100, v153
	v_mul_f32_e32 v153, v152, v21
	v_mul_f32_e32 v101, v101, v153
	v_mul_f32_e32 v153, v152, v22
	v_mul_f32_e32 v102, v102, v153
	v_mul_f32_e32 v153, v152, v23
	v_mul_f32_e32 v103, v103, v153
	global_store_dwordx4 v4, v[100:103], s[6:7] offset:3072
	s_waitcnt vmcnt(28)
; __device__ __forceinline__ void phase_final(KP kp_){ asm volatile("" : "+s"(kp_)); const Params p=load_params(kp_);
;     ...
;   for (int r=blockIdx.x*8+wid; r<16384; r+=gridDim.x*8){
;     float4 xv[4]; float ss=0.f;
;     for(int i=0;i<4;++i){ xv[i]=*(const float4*)(p.out+(size_t)r*1024+lane*4+256*i); ss+=xv[i].x*xv[i].x+xv[i].y*xv[i].y+xv[i].z*xv[i].z+xv[i].w*xv[i].w; }
;     ss=wave_sum(ss); float rstd=rsqrtf(ss*(1.f/1024.f)+EPSV);
;     for(int i=0;i<4;++i){ int col=lane*4+256*i; float4 v=xv[i]; float4 g=*(const float4*)(p.final_g+col);
;       v.x*=rstd*g.x; v.y*=rstd*g.y; v.z*=rstd*g.z; v.w*=rstd*g.w; *(float4*)(p.out+(size_t)r*1024+col)=v; }
	v_mul_f32_e32 v5, v104, v104
	v_fmac_f32_e32 v5, v105, v105
	v_fmac_f32_e32 v5, v106, v106
	v_fmac_f32_e32 v5, v107, v107
	v_fmac_f32_e32 v5, v108, v108
	v_fmac_f32_e32 v5, v109, v109
	v_fmac_f32_e32 v5, v110, v110
	v_fmac_f32_e32 v5, v111, v111
	v_fmac_f32_e32 v5, v112, v112
	v_fmac_f32_e32 v5, v113, v113
	v_fmac_f32_e32 v5, v114, v114
	v_fmac_f32_e32 v5, v115, v115
	v_fmac_f32_e32 v5, v116, v116
	v_fmac_f32_e32 v5, v117, v117
	v_fmac_f32_e32 v5, v118, v118
	v_fmac_f32_e32 v5, v119, v119
	s_nop 1
	v_add_f32_dpp v5, v5, v5 row_ror:8 row_mask:0xf bank_mask:0xf
	s_nop 1
	v_add_f32_dpp v5, v5, v5 row_ror:4 row_mask:0xf bank_mask:0xf
	s_nop 1
	v_add_f32_dpp v5, v5, v5 row_ror:2 row_mask:0xf bank_mask:0xf
	s_nop 1
	v_add_f32_dpp v5, v5, v5 row_ror:1 row_mask:0xf bank_mask:0xf
	s_nop 1
	v_readlane_b32 s8, v5, 0
	v_readlane_b32 s9, v5, 16
	v_readlane_b32 s10, v5, 32
	v_readlane_b32 s11, v5, 48
	s_nop 1
	v_mov_b32_e32 v7, s8
	v_add_f32_e32 v7, s9, v7
	v_add_f32_e32 v7, s10, v7
	v_add_f32_e32 v7, s11, v7
	v_fmamk_f32 v7, v7, 0x3a800000, v6
	v_rsq_f32_e32 v152, v7
	s_nop 0
	s_add_u32 s6, s2, 0x2800000
	s_addc_u32 s7, s3, 0
	v_mul_f32_e32 v153, v152, v8
	v_mul_f32_e32 v104, v104, v153
	v_mul_f32_e32 v153, v152, v9
	v_mul_f32_e32 v105, v105, v153
	v_mul_f32_e32 v153, v152, v10
	v_mul_f32_e32 v106, v106, v153
	v_mul_f32_e32 v153, v152, v11
	v_mul_f32_e32 v107, v107, v153
	global_store_dwordx4 v4, v[104:107], s[6:7] offset:0
	v_mul_f32_e32 v153, v152, v12
	v_mul_f32_e32 v108, v108, v153
	v_mul_f32_e32 v153, v152, v13
	v_mul_f32_e32 v109, v109, v153
	v_mul_f32_e32 v153, v152, v14
	v_mul_f32_e32 v110, v110, v153
	v_mul_f32_e32 v153, v152, v15
	v_mul_f32_e32 v111, v111, v153
	global_store_dwordx4 v4, v[108:111], s[6:7] offset:1024
	v_mul_f32_e32 v153, v152, v16
	v_mul_f32_e32 v112, v112, v153
	v_mul_f32_e32 v153, v152, v17
	v_mul_f32_e32 v113, v113, v153
	v_mul_f32_e32 v153, v152, v18
	v_mul_f32_e32 v114, v114, v153
	v_mul_f32_e32 v153, v152, v19
	v_mul_f32_e32 v115, v115, v153
	global_store_dwordx4 v4, v[112:115], s[6:7] offset:2048
	v_mul_f32_e32 v153, v152, v20
	v_mul_f32_e32 v116, v116, v153
	v_mul_f32_e32 v153, v152, v21
	v_mul_f32_e32 v117, v117, v153
	v_mul_f32_e32 v153, v152, v22
	v_mul_f32_e32 v118, v118, v153
	v_mul_f32_e32 v153, v152, v23
	v_mul_f32_e32 v119, v119, v153
	global_store_dwordx4 v4, v[116:119], s[6:7] offset:3072
	s_waitcnt vmcnt(28)
; __device__ __forceinline__ void phase_final(KP kp_){ asm volatile("" : "+s"(kp_)); const Params p=load_params(kp_);
;     ...
;   for (int r=blockIdx.x*8+wid; r<16384; r+=gridDim.x*8){
;     float4 xv[4]; float ss=0.f;
;     for(int i=0;i<4;++i){ xv[i]=*(const float4*)(p.out+(size_t)r*1024+lane*4+256*i); ss+=xv[i].x*xv[i].x+xv[i].y*xv[i].y+xv[i].z*xv[i].z+xv[i].w*xv[i].w; }
;     ss=wave_sum(ss); float rstd=rsqrtf(ss*(1.f/1024.f)+EPSV);
;     for(int i=0;i<4;++i){ int col=lane*4+256*i; float4 v=xv[i]; float4 g=*(const float4*)(p.final_g+col);
;       v.x*=rstd*g.x; v.y*=rstd*g.y; v.z*=rstd*g.z; v.w*=rstd*g.w; *(float4*)(p.out+(size_t)r*1024+col)=v; }
	v_mul_f32_e32 v5, v120, v120
	v_fmac_f32_e32 v5, v121, v121
	v_fmac_f32_e32 v5, v122, v122
	v_fmac_f32_e32 v5, v123, v123
	v_fmac_f32_e32 v5, v124, v124
	v_fmac_f32_e32 v5, v125, v125
	v_fmac_f32_e32 v5, v126, v126
	v_fmac_f32_e32 v5, v127, v127
	v_fmac_f32_e32 v5, v128, v128
	v_fmac_f32_e32 v5, v129, v129
	v_fmac_f32_e32 v5, v130, v130
	v_fmac_f32_e32 v5, v131, v131
	v_fmac_f32_e32 v5, v132, v132
	v_fmac_f32_e32 v5, v133, v133
	v_fmac_f32_e32 v5, v134, v134
	v_fmac_f32_e32 v5, v135, v135
	s_nop 1
	v_add_f32_dpp v5, v5, v5 row_ror:8 row_mask:0xf bank_mask:0xf
	s_nop 1
	v_add_f32_dpp v5, v5, v5 row_ror:4 row_mask:0xf bank_mask:0xf
	s_nop 1
	v_add_f32_dpp v5, v5, v5 row_ror:2 row_mask:0xf bank_mask:0xf
	s_nop 1
	v_add_f32_dpp v5, v5, v5 row_ror:1 row_mask:0xf bank_mask:0xf
	s_nop 1
	v_readlane_b32 s8, v5, 0
	v_readlane_b32 s9, v5, 16
	v_readlane_b32 s10, v5, 32
	v_readlane_b32 s11, v5, 48
	s_nop 1
	v_mov_b32_e32 v7, s8
	v_add_f32_e32 v7, s9, v7
	v_add_f32_e32 v7, s10, v7
	v_add_f32_e32 v7, s11, v7
	v_fmamk_f32 v7, v7, 0x3a800000, v6
	v_rsq_f32_e32 v152, v7
	s_nop 0
	s_add_u32 s6, s2, 0x3000000
	s_addc_u32 s7, s3, 0
	v_mul_f32_e32 v153, v152, v8
	v_mul_f32_e32 v120, v120, v153
	v_mul_f32_e32 v153, v152, v9
	v_mul_f32_e32 v121, v121, v153
	v_mul_f32_e32 v153, v152, v10
	v_mul_f32_e32 v122, v122, v153
	v_mul_f32_e32 v153, v152, v11
	v_mul_f32_e32 v123, v123, v153
	global_store_dwordx4 v4, v[120:123], s[6:7] offset:0
	v_mul_f32_e32 v153, v152, v12
	v_mul_f32_e32 v124, v124, v153
	v_mul_f32_e32 v153, v152, v13
	v_mul_f32_e32 v125, v125, v153
	v_mul_f32_e32 v153, v152, v14
	v_mul_f32_e32 v126, v126, v153
	v_mul_f32_e32 v153, v152, v15
	v_mul_f32_e32 v127, v127, v153
	global_store_dwordx4 v4, v[124:127], s[6:7] offset:1024
	v_mul_f32_e32 v153, v152, v16
	v_mul_f32_e32 v128, v128, v153
	v_mul_f32_e32 v153, v152, v17
	v_mul_f32_e32 v129, v129, v153
	v_mul_f32_e32 v153, v152, v18
	v_mul_f32_e32 v130, v130, v153
	v_mul_f32_e32 v153, v152, v19
	v_mul_f32_e32 v131, v131, v153
	global_store_dwordx4 v4, v[128:131], s[6:7] offset:2048
	v_mul_f32_e32 v153, v152, v20
	v_mul_f32_e32 v132, v132, v153
	v_mul_f32_e32 v153, v152, v21
	v_mul_f32_e32 v133, v133, v153
	v_mul_f32_e32 v153, v152, v22
	v_mul_f32_e32 v134, v134, v153
	v_mul_f32_e32 v153, v152, v23
	v_mul_f32_e32 v135, v135, v153
	global_store_dwordx4 v4, v[132:135], s[6:7] offset:3072
	s_waitcnt vmcnt(28)
	v_mul_f32_e32 v5, v136, v136
	v_fmac_f32_e32 v5, v137, v137
	v_fmac_f32_e32 v5, v138, v138
	v_fmac_f32_e32 v5, v139, v139
	v_fmac_f32_e32 v5, v140, v140
	v_fmac_f32_e32 v5, v141, v141
	v_fmac_f32_e32 v5, v142, v142
	v_fmac_f32_e32 v5, v143, v143
	v_fmac_f32_e32 v5, v144, v144
	v_fmac_f32_e32 v5, v145, v145
	v_fmac_f32_e32 v5, v146, v146
	v_fmac_f32_e32 v5, v147, v147
	v_fmac_f32_e32 v5, v148, v148
	v_fmac_f32_e32 v5, v149, v149
	v_fmac_f32_e32 v5, v150, v150
	v_fmac_f32_e32 v5, v151, v151
	s_nop 1
	v_add_f32_dpp v5, v5, v5 row_ror:8 row_mask:0xf bank_mask:0xf
	s_nop 1
	v_add_f32_dpp v5, v5, v5 row_ror:4 row_mask:0xf bank_mask:0xf
	s_nop 1
	v_add_f32_dpp v5, v5, v5 row_ror:2 row_mask:0xf bank_mask:0xf
	s_nop 1
	v_add_f32_dpp v5, v5, v5 row_ror:1 row_mask:0xf bank_mask:0xf
	s_nop 1
	v_readlane_b32 s8, v5, 0
	v_readlane_b32 s9, v5, 16
	v_readlane_b32 s10, v5, 32
	v_readlane_b32 s11, v5, 48
	s_nop 1
	v_mov_b32_e32 v7, s8
	v_add_f32_e32 v7, s9, v7
	v_add_f32_e32 v7, s10, v7
	v_add_f32_e32 v7, s11, v7
	v_fmamk_f32 v7, v7, 0x3a800000, v6
	v_rsq_f32_e32 v152, v7
	s_nop 0
	s_add_u32 s6, s2, 0x3800000
	s_addc_u32 s7, s3, 0
	v_mul_f32_e32 v153, v152, v8
	v_mul_f32_e32 v136, v136, v153
	v_mul_f32_e32 v153, v152, v9
	v_mul_f32_e32 v137, v137, v153
	v_mul_f32_e32 v153, v152, v10
	v_mul_f32_e32 v138, v138, v153
	v_mul_f32_e32 v153, v152, v11
	v_mul_f32_e32 v139, v139, v153
	global_store_dwordx4 v4, v[136:139], s[6:7] offset:0
	v_mul_f32_e32 v153, v152, v12
	v_mul_f32_e32 v140, v140, v153
	v_mul_f32_e32 v153, v152, v13
	v_mul_f32_e32 v141, v141, v153
	v_mul_f32_e32 v153, v152, v14
	v_mul_f32_e32 v142, v142, v153
	v_mul_f32_e32 v153, v152, v15
	v_mul_f32_e32 v143, v143, v153
	global_store_dwordx4 v4, v[140:143], s[6:7] offset:1024
	v_mul_f32_e32 v153, v152, v16
	v_mul_f32_e32 v144, v144, v153
	v_mul_f32_e32 v153, v152, v17
	v_mul_f32_e32 v145, v145, v153
	v_mul_f32_e32 v153, v152, v18
	v_mul_f32_e32 v146, v146, v153
	v_mul_f32_e32 v153, v152, v19
	v_mul_f32_e32 v147, v147, v153
	global_store_dwordx4 v4, v[144:147], s[6:7] offset:2048
	v_mul_f32_e32 v153, v152, v20
	v_mul_f32_e32 v148, v148, v153
	v_mul_f32_e32 v153, v152, v21
	v_mul_f32_e32 v149, v149, v153
	v_mul_f32_e32 v153, v152, v22
	v_mul_f32_e32 v150, v150, v153
	v_mul_f32_e32 v153, v152, v23
	v_mul_f32_e32 v151, v151, v153
	global_store_dwordx4 v4, v[148:151], s[6:7] offset:3072
	s_nop 1
